# v155 + residual epilogue: row groups 4-6 loads issued up front with groups 1-3 (12 loads in flight), vmcnt waits re-derived
# baseline (speedup 1.0000x reference)
.LBB0_212:
	s_mov_b64 s[0:1], 0
	s_cbranch_execz .LBB0_210
	s_waitcnt lgkmcnt(0)
	v_lshlrev_b64 v[144:145], 1, v[220:221]
	v_lshl_add_u64 v[172:173], v[136:137], 0, v[144:145]
	global_load_dwordx4 v[164:167], v[172:173], off
	global_load_dwordx4 v[160:163], v[172:173], off offset:256
	v_ashrrev_i32_e32 v227, 31, v226
	v_ashrrev_i32_e32 v223, 31, v222
	v_lshlrev_b64 v[146:147], 12, v[226:227]
	v_lshlrev_b64 v[148:149], 12, v[222:223]
	v_lshl_add_u64 v[146:147], s[16:17], 0, v[146:147]
	v_lshl_add_u64 v[148:149], s[16:17], 0, v[148:149]
	v_lshl_add_u64 v[170:171], v[146:147], 0, v[144:145]
	v_lshl_add_u64 v[168:169], v[148:149], 0, v[144:145]
	global_load_dwordx4 v[156:159], v[170:171], off
	global_load_dwordx4 v[152:155], v[170:171], off offset:256
	global_load_dwordx4 v[148:151], v[168:169], off
	global_load_dwordx4 v[144:147], v[168:169], off offset:256
	v_add_co_u32_e32 v184, vcc, 0x30000, v172
	s_nop 1
	v_addc_co_u32_e32 v185, vcc, 0, v173, vcc
	global_load_dwordx4 v[188:191], v[184:185], off offset:256
	global_load_dwordx4 v[184:187], v[184:185], off
	v_add_co_u32_e32 v210, vcc, 0x80000, v172
	s_nop 1
	v_addc_co_u32_e32 v211, vcc, 0, v173, vcc
	global_load_dwordx4 v[214:217], v[210:211], off offset:256
	global_load_dwordx4 v[210:213], v[210:211], off
	v_add_co_u32_e32 v194, vcc, 0x90000, v172
	s_nop 1
	v_addc_co_u32_e32 v195, vcc, 0, v173, vcc
	global_load_dwordx4 v[230:233], v[194:195], off offset:256
	global_load_dwordx4 v[194:197], v[194:195], off
	v_pk_add_f32 v[142:143], v[142:143], v[98:99]
	v_pk_add_f32 v[138:139], v[138:139], v[90:91]
	v_pk_add_f32 v[134:135], v[134:135], v[102:103]
	v_pk_add_f32 v[130:131], v[130:131], v[94:95]
	v_cmp_lt_i32_e32 vcc, v243, v238
	s_lshl_b32 s4, s66, 2
	s_ashr_i32 s5, s4, 31
	v_cndmask_b32_e32 v174, v237, v243, vcc
	v_lshlrev_b32_e32 v174, 2, v174
	v_cmp_lt_i32_e32 vcc, v244, v238
	s_waitcnt vmcnt(11)
	v_lshlrev_b32_e32 v176, 16, v164
	v_and_b32_e32 v177, 0xffff0000, v164
	v_lshlrev_b32_e32 v164, 16, v165
	v_and_b32_e32 v165, 0xffff0000, v165
	v_lshlrev_b32_e32 v178, 16, v166
	v_and_b32_e32 v179, 0xffff0000, v166
	v_lshlrev_b32_e32 v166, 16, v167
	v_and_b32_e32 v167, 0xffff0000, v167
	s_waitcnt vmcnt(10)
	v_lshlrev_b32_e32 v180, 16, v160
	v_and_b32_e32 v181, 0xffff0000, v160
	v_lshlrev_b32_e32 v160, 16, v161
	v_and_b32_e32 v161, 0xffff0000, v161
	v_lshlrev_b32_e32 v182, 16, v162
	v_and_b32_e32 v183, 0xffff0000, v162
	v_lshlrev_b32_e32 v162, 16, v163
	v_and_b32_e32 v163, 0xffff0000, v163
	v_pk_add_f32 v[142:143], v[142:143], v[164:165]
	v_pk_add_f32 v[164:165], v[228:229], v[176:177]
	v_pk_add_f32 v[138:139], v[138:139], v[166:167]
	v_pk_add_f32 v[140:141], v[140:141], v[178:179]
	v_pk_add_f32 v[134:135], v[134:135], v[160:161]
	v_pk_add_f32 v[132:133], v[132:133], v[180:181]
	v_pk_add_f32 v[160:161], v[130:131], v[162:163]
	v_pk_add_f32 v[162:163], v[128:129], v[182:183]
	v_cvt_pk_bf16_f32 v128, v164, v165
	v_cvt_pk_bf16_f32 v129, v142, v143
	v_mul_f32_e32 v130, v165, v165
	v_mul_f32_e32 v131, v143, v143
	v_mul_f32_e32 v143, v141, v141
	v_mul_f32_e32 v165, v139, v139
	v_mul_f32_e32 v166, v133, v133
	v_mul_f32_e32 v167, v135, v135
	v_mul_f32_e32 v176, v163, v163
	v_mul_f32_e32 v177, v161, v161
	v_fmac_f32_e32 v130, v164, v164
	v_fmac_f32_e32 v131, v142, v142
	v_fmac_f32_e32 v143, v140, v140
	v_fmac_f32_e32 v165, v138, v138
	v_fmac_f32_e32 v166, v132, v132
	v_fmac_f32_e32 v167, v134, v134
	v_fmac_f32_e32 v176, v162, v162
	v_fmac_f32_e32 v177, v160, v160
	v_add_f32_e32 v130, v130, v131
	v_add_f32_e32 v131, v143, v165
	v_add_f32_e32 v142, v166, v167
	v_add_f32_e32 v143, v176, v177
	v_add_f32_e32 v130, v130, v131
	v_add_f32_e32 v131, v142, v143
	v_add_f32_e32 v142, v130, v131
	ds_bpermute_b32 v143, v174, v142
	v_cndmask_b32_e32 v175, v237, v244, vcc
	v_cvt_pk_bf16_f32 v130, v140, v141
	v_cvt_pk_bf16_f32 v131, v138, v139
	global_store_dwordx4 v[172:173], v[128:131], off
	s_waitcnt lgkmcnt(0)
	s_nop 0
	v_add_f32_e32 v128, v142, v143
	v_lshlrev_b32_e32 v142, 2, v175
	ds_bpermute_b32 v129, v142, v128
	v_cvt_pk_bf16_f32 v130, v132, v133
	v_cvt_pk_bf16_f32 v131, v134, v135
	v_cvt_pk_bf16_f32 v132, v162, v163
	v_cvt_pk_bf16_f32 v133, v160, v161
	global_store_dwordx4 v[172:173], v[130:133], off offset:256
	s_and_saveexec_b64 s[0:1], s[42:43]
	s_cbranch_execz .LBB0_215
	v_lshlrev_b64 v[130:131], 7, v[224:225]
	v_lshl_add_u64 v[130:131], s[14:15], 0, v[130:131]
	v_lshl_add_u64 v[130:131], s[4:5], 2, v[130:131]
	s_lshl_b32 s22, s57, 2
	v_lshl_add_u64 v[130:131], v[130:131], 0, s[22:23]
	s_waitcnt lgkmcnt(0)
	v_add_f32_e32 v128, v128, v129
	global_store_dword v[130:131], v128, off
.LBB0_215:
	s_or_b64 exec, exec, s[0:1]
	v_or_b32_e32 v138, 48, v224
	v_ashrrev_i32_e32 v139, 31, v138
	s_waitcnt lgkmcnt(0)
	v_lshlrev_b64 v[128:129], 12, v[138:139]
	v_lshl_add_u64 v[128:129], s[16:17], 0, v[128:129]
	v_lshl_add_u64 v[140:141], v[220:221], 1, v[128:129]
	s_waitcnt vmcnt(11)
	v_lshlrev_b32_e32 v160, 16, v156
	v_and_b32_e32 v161, 0xffff0000, v156
	v_pk_add_f32 v[124:125], v[124:125], v[96:97]
	v_lshlrev_b32_e32 v156, 16, v157
	v_and_b32_e32 v157, 0xffff0000, v157
	v_lshlrev_b32_e32 v162, 16, v158
	v_and_b32_e32 v163, 0xffff0000, v158
	v_lshlrev_b32_e32 v158, 16, v159
	v_and_b32_e32 v159, 0xffff0000, v159
	v_pk_add_f32 v[126:127], v[126:127], v[98:99]
	v_pk_add_f32 v[124:125], v[124:125], v[160:161]
	v_pk_add_f32 v[122:123], v[122:123], v[90:91]
	v_pk_add_f32 v[120:121], v[120:121], v[88:89]
	v_pk_add_f32 v[126:127], v[126:127], v[156:157]
	v_pk_add_f32 v[156:157], v[122:123], v[158:159]
	v_pk_add_f32 v[122:123], v[120:121], v[162:163]
	v_cvt_pk_bf16_f32 v120, v124, v125
	v_mul_f32_e32 v125, v125, v125
	v_fmac_f32_e32 v125, v124, v124
	v_mul_f32_e32 v124, v127, v127
	v_fmac_f32_e32 v124, v126, v126
	v_cvt_pk_bf16_f32 v121, v126, v127
	v_add_f32_e32 v124, v125, v124
	v_mul_f32_e32 v125, v123, v123
	v_mul_f32_e32 v126, v157, v157
	v_fmac_f32_e32 v125, v122, v122
	v_fmac_f32_e32 v126, v156, v156
	v_add_f32_e32 v125, v125, v126
	v_add_f32_e32 v143, v124, v125
	s_waitcnt vmcnt(10)
	v_lshlrev_b32_e32 v124, 16, v152
	v_and_b32_e32 v125, 0xffff0000, v152
	v_lshlrev_b32_e32 v126, 16, v153
	v_and_b32_e32 v127, 0xffff0000, v153
	v_pk_add_f32 v[118:119], v[118:119], v[102:103]
	v_pk_add_f32 v[116:117], v[116:117], v[100:101]
	v_lshlrev_b32_e32 v152, 16, v154
	v_and_b32_e32 v153, 0xffff0000, v154
	v_pk_add_f32 v[118:119], v[118:119], v[126:127]
	v_pk_add_f32 v[116:117], v[116:117], v[124:125]
	v_pk_add_f32 v[112:113], v[112:113], v[92:93]
	v_lshlrev_b32_e32 v154, 16, v155
	v_and_b32_e32 v155, 0xffff0000, v155
	v_pk_add_f32 v[114:115], v[114:115], v[94:95]
	v_pk_add_f32 v[126:127], v[112:113], v[152:153]
	v_mul_f32_e32 v112, v117, v117
	v_mul_f32_e32 v113, v119, v119
	v_pk_add_f32 v[124:125], v[114:115], v[154:155]
	v_fmac_f32_e32 v112, v116, v116
	v_fmac_f32_e32 v113, v118, v118
	v_add_f32_e32 v112, v112, v113
	v_mul_f32_e32 v113, v127, v127
	v_mul_f32_e32 v114, v125, v125
	v_fmac_f32_e32 v113, v126, v126
	v_fmac_f32_e32 v114, v124, v124
	v_add_f32_e32 v113, v113, v114
	v_add_f32_e32 v112, v112, v113
	v_add_f32_e32 v112, v143, v112
	ds_bpermute_b32 v113, v174, v112
	v_cvt_pk_bf16_f32 v122, v122, v123
	v_cvt_pk_bf16_f32 v123, v156, v157
	global_store_dwordx4 v[170:171], v[120:123], off
	v_cvt_pk_bf16_f32 v114, v116, v117
	s_waitcnt lgkmcnt(0)
	v_add_f32_e32 v112, v112, v113
	ds_bpermute_b32 v113, v142, v112
	v_cvt_pk_bf16_f32 v115, v118, v119
	v_cvt_pk_bf16_f32 v116, v126, v127
	v_cvt_pk_bf16_f32 v117, v124, v125
	global_store_dwordx4 v[170:171], v[114:117], off offset:256
	s_and_saveexec_b64 s[0:1], s[42:43]
	s_cbranch_execz .LBB0_217
	v_lshlrev_b64 v[114:115], 7, v[226:227]
	v_lshl_add_u64 v[114:115], s[14:15], 0, v[114:115]
	v_lshl_add_u64 v[114:115], s[4:5], 2, v[114:115]
	s_lshl_b32 s22, s57, 2
	v_lshl_add_u64 v[114:115], v[114:115], 0, s[22:23]
	s_waitcnt lgkmcnt(0)
	v_add_f32_e32 v112, v112, v113
	global_store_dword v[114:115], v112, off
.LBB0_217:
	s_or_b64 exec, exec, s[0:1]
	v_add_u32_e32 v120, 0x80, v224
	v_ashrrev_i32_e32 v121, 31, v120
	s_waitcnt lgkmcnt(0)
	v_lshlrev_b64 v[112:113], 12, v[120:121]
	v_lshl_add_u64 v[112:113], s[16:17], 0, v[112:113]
	v_lshl_add_u64 v[122:123], v[220:221], 1, v[112:113]
	s_waitcnt vmcnt(11)
	v_lshlrev_b32_e32 v124, 16, v148
	v_and_b32_e32 v125, 0xffff0000, v148
	v_pk_add_f32 v[108:109], v[108:109], v[96:97]
	v_lshlrev_b32_e32 v126, 16, v149
	v_and_b32_e32 v127, 0xffff0000, v149
	v_lshlrev_b32_e32 v148, 16, v150
	v_and_b32_e32 v149, 0xffff0000, v150
	v_lshlrev_b32_e32 v150, 16, v151
	v_and_b32_e32 v151, 0xffff0000, v151
	v_pk_add_f32 v[110:111], v[110:111], v[98:99]
	v_pk_add_f32 v[108:109], v[108:109], v[124:125]
	v_pk_add_f32 v[106:107], v[106:107], v[90:91]
	v_pk_add_f32 v[104:105], v[104:105], v[88:89]
	v_pk_add_f32 v[110:111], v[110:111], v[126:127]
	v_pk_add_f32 v[124:125], v[106:107], v[150:151]
	v_pk_add_f32 v[106:107], v[104:105], v[148:149]
	v_cvt_pk_bf16_f32 v104, v108, v109
	v_mul_f32_e32 v109, v109, v109
	v_fmac_f32_e32 v109, v108, v108
	v_mul_f32_e32 v108, v111, v111
	v_fmac_f32_e32 v108, v110, v110
	v_cvt_pk_bf16_f32 v105, v110, v111
	v_add_f32_e32 v108, v109, v108
	v_mul_f32_e32 v109, v107, v107
	v_mul_f32_e32 v110, v125, v125
	v_fmac_f32_e32 v109, v106, v106
	v_fmac_f32_e32 v110, v124, v124
	v_add_f32_e32 v109, v109, v110
	v_add_f32_e32 v143, v108, v109
	s_waitcnt vmcnt(10)
	v_lshlrev_b32_e32 v108, 16, v144
	v_and_b32_e32 v109, 0xffff0000, v144
	v_lshlrev_b32_e32 v110, 16, v145
	v_and_b32_e32 v111, 0xffff0000, v145
	v_pk_add_f32 v[86:87], v[86:87], v[102:103]
	v_pk_add_f32 v[84:85], v[84:85], v[100:101]
	v_lshlrev_b32_e32 v126, 16, v146
	v_and_b32_e32 v127, 0xffff0000, v146
	v_pk_add_f32 v[86:87], v[86:87], v[110:111]
	v_pk_add_f32 v[84:85], v[84:85], v[108:109]
	v_pk_add_f32 v[80:81], v[80:81], v[92:93]
	v_lshlrev_b32_e32 v144, 16, v147
	v_and_b32_e32 v145, 0xffff0000, v147
	v_pk_add_f32 v[82:83], v[82:83], v[94:95]
	v_pk_add_f32 v[110:111], v[80:81], v[126:127]
	v_mul_f32_e32 v80, v85, v85
	v_mul_f32_e32 v81, v87, v87
	v_pk_add_f32 v[108:109], v[82:83], v[144:145]
	v_fmac_f32_e32 v80, v84, v84
	v_fmac_f32_e32 v81, v86, v86
	v_add_f32_e32 v80, v80, v81
	v_mul_f32_e32 v81, v111, v111
	v_mul_f32_e32 v82, v109, v109
	v_fmac_f32_e32 v81, v110, v110
	v_fmac_f32_e32 v82, v108, v108
	v_add_f32_e32 v81, v81, v82
	v_add_f32_e32 v80, v80, v81
	v_add_f32_e32 v80, v143, v80
	ds_bpermute_b32 v81, v174, v80
	v_cvt_pk_bf16_f32 v106, v106, v107
	v_cvt_pk_bf16_f32 v107, v124, v125
	global_store_dwordx4 v[168:169], v[104:107], off
	v_cvt_pk_bf16_f32 v82, v84, v85
	s_waitcnt lgkmcnt(0)
	v_add_f32_e32 v80, v80, v81
	ds_bpermute_b32 v81, v142, v80
	v_cvt_pk_bf16_f32 v83, v86, v87
	v_cvt_pk_bf16_f32 v84, v110, v111
	v_cvt_pk_bf16_f32 v85, v108, v109
	global_store_dwordx4 v[168:169], v[82:85], off offset:256
	s_and_saveexec_b64 s[0:1], s[42:43]
	s_cbranch_execz .LBB0_219
	v_lshlrev_b64 v[82:83], 7, v[222:223]
	v_lshl_add_u64 v[82:83], s[14:15], 0, v[82:83]
	v_lshl_add_u64 v[82:83], s[4:5], 2, v[82:83]
	s_lshl_b32 s22, s57, 2
	v_lshl_add_u64 v[82:83], v[82:83], 0, s[22:23]
	s_waitcnt lgkmcnt(0)
	v_add_f32_e32 v80, v80, v81
	global_store_dword v[82:83], v80, off
.LBB0_219:
	s_or_b64 exec, exec, s[0:1]
	s_waitcnt lgkmcnt(0)
	v_lshl_add_u64 v[80:81], v[220:221], 1, v[136:137]
	s_mov_b64 s[0:1], 0x90000
	v_lshl_add_u64 v[104:105], v[80:81], 0, s[0:1]
	v_add_co_u32_e32 v80, vcc, 0x90000, v80
	s_waitcnt vmcnt(10)
	v_lshlrev_b32_e32 v106, 16, v184
	v_addc_co_u32_e32 v81, vcc, 0, v81, vcc
	s_nop 0
	v_and_b32_e32 v107, 0xffff0000, v184
	v_pk_add_f32 v[76:77], v[76:77], v[96:97]
	v_lshlrev_b32_e32 v108, 16, v185
	v_and_b32_e32 v109, 0xffff0000, v185
	v_lshlrev_b32_e32 v110, 16, v186
	v_and_b32_e32 v111, 0xffff0000, v186
	v_lshlrev_b32_e32 v124, 16, v187
	v_and_b32_e32 v125, 0xffff0000, v187
	v_pk_add_f32 v[78:79], v[78:79], v[98:99]
	v_pk_add_f32 v[76:77], v[76:77], v[106:107]
	v_pk_add_f32 v[74:75], v[74:75], v[90:91]
	v_pk_add_f32 v[72:73], v[72:73], v[88:89]
	v_pk_add_f32 v[78:79], v[78:79], v[108:109]
	v_pk_add_f32 v[106:107], v[74:75], v[124:125]
	v_pk_add_f32 v[74:75], v[72:73], v[110:111]
	v_cvt_pk_bf16_f32 v72, v76, v77
	v_mul_f32_e32 v77, v77, v77
	v_fmac_f32_e32 v77, v76, v76
	v_mul_f32_e32 v76, v79, v79
	v_fmac_f32_e32 v76, v78, v78
	v_cvt_pk_bf16_f32 v73, v78, v79
	v_add_f32_e32 v76, v77, v76
	v_mul_f32_e32 v77, v75, v75
	v_mul_f32_e32 v78, v107, v107
	v_fmac_f32_e32 v77, v74, v74
	v_fmac_f32_e32 v78, v106, v106
	v_add_f32_e32 v77, v77, v78
	v_add_f32_e32 v124, v76, v77
	v_lshlrev_b32_e32 v76, 16, v188
	v_and_b32_e32 v77, 0xffff0000, v188
	v_lshlrev_b32_e32 v78, 16, v189
	v_and_b32_e32 v79, 0xffff0000, v189
	v_pk_add_f32 v[70:71], v[70:71], v[102:103]
	v_pk_add_f32 v[68:69], v[68:69], v[100:101]
	v_lshlrev_b32_e32 v108, 16, v190
	v_and_b32_e32 v109, 0xffff0000, v190
	v_pk_add_f32 v[70:71], v[70:71], v[78:79]
	v_pk_add_f32 v[68:69], v[68:69], v[76:77]
	v_pk_add_f32 v[64:65], v[64:65], v[92:93]
	v_lshlrev_b32_e32 v110, 16, v191
	v_and_b32_e32 v111, 0xffff0000, v191
	v_pk_add_f32 v[66:67], v[66:67], v[94:95]
	v_pk_add_f32 v[78:79], v[64:65], v[108:109]
	v_mul_f32_e32 v64, v69, v69
	v_mul_f32_e32 v65, v71, v71
	v_pk_add_f32 v[76:77], v[66:67], v[110:111]
	v_fmac_f32_e32 v64, v68, v68
	v_fmac_f32_e32 v65, v70, v70
	v_add_f32_e32 v64, v64, v65
	v_mul_f32_e32 v65, v79, v79
	v_mul_f32_e32 v66, v77, v77
	v_fmac_f32_e32 v65, v78, v78
	v_fmac_f32_e32 v66, v76, v76
	v_add_f32_e32 v65, v65, v66
	v_add_f32_e32 v64, v64, v65
	v_add_f32_e32 v64, v124, v64
	ds_bpermute_b32 v65, v174, v64
	v_cvt_pk_bf16_f32 v74, v74, v75
	v_cvt_pk_bf16_f32 v75, v106, v107
	global_store_dwordx4 v[140:141], v[72:75], off
	v_cvt_pk_bf16_f32 v66, v68, v69
	s_waitcnt lgkmcnt(0)
	v_add_f32_e32 v64, v64, v65
	ds_bpermute_b32 v65, v142, v64
	v_cvt_pk_bf16_f32 v67, v70, v71
	v_cvt_pk_bf16_f32 v68, v78, v79
	v_cvt_pk_bf16_f32 v69, v76, v77
	global_store_dwordx4 v[140:141], v[66:69], off offset:256
	s_and_saveexec_b64 s[0:1], s[42:43]
	s_cbranch_execz .LBB0_221
	v_lshlrev_b64 v[66:67], 7, v[138:139]
	v_lshl_add_u64 v[66:67], s[14:15], 0, v[66:67]
	v_lshl_add_u64 v[66:67], s[4:5], 2, v[66:67]
	s_lshl_b32 s22, s57, 2
	v_lshl_add_u64 v[66:67], v[66:67], 0, s[22:23]
	s_waitcnt lgkmcnt(0)
	v_add_f32_e32 v64, v64, v65
	global_store_dword v[66:67], v64, off
.LBB0_221:
	s_or_b64 exec, exec, s[0:1]
	v_or_b32_e32 v72, 32, v120
	v_ashrrev_i32_e32 v73, 31, v72
	s_waitcnt lgkmcnt(0)
	v_lshlrev_b64 v[64:65], 12, v[72:73]
	v_lshl_add_u64 v[64:65], s[16:17], 0, v[64:65]
	v_lshl_add_u64 v[74:75], v[220:221], 1, v[64:65]
	global_load_dwordx4 v[68:71], v[74:75], off
	global_load_dwordx4 v[64:67], v[74:75], off offset:256
	s_waitcnt vmcnt(12)
	v_lshlrev_b32_e32 v76, 16, v210
	v_and_b32_e32 v77, 0xffff0000, v210
	v_pk_add_f32 v[60:61], v[60:61], v[96:97]
	v_lshlrev_b32_e32 v78, 16, v211
	v_and_b32_e32 v79, 0xffff0000, v211
	v_lshlrev_b32_e32 v106, 16, v212
	v_and_b32_e32 v107, 0xffff0000, v212
	v_lshlrev_b32_e32 v108, 16, v213
	v_and_b32_e32 v109, 0xffff0000, v213
	v_pk_add_f32 v[62:63], v[62:63], v[98:99]
	v_pk_add_f32 v[60:61], v[60:61], v[76:77]
	v_pk_add_f32 v[58:59], v[58:59], v[90:91]
	v_pk_add_f32 v[56:57], v[56:57], v[88:89]
	v_pk_add_f32 v[62:63], v[62:63], v[78:79]
	v_pk_add_f32 v[76:77], v[58:59], v[108:109]
	v_pk_add_f32 v[58:59], v[56:57], v[106:107]
	v_cvt_pk_bf16_f32 v56, v60, v61
	v_mul_f32_e32 v61, v61, v61
	v_fmac_f32_e32 v61, v60, v60
	v_mul_f32_e32 v60, v63, v63
	v_fmac_f32_e32 v60, v62, v62
	v_cvt_pk_bf16_f32 v57, v62, v63
	v_add_f32_e32 v60, v61, v60
	v_mul_f32_e32 v61, v59, v59
	v_mul_f32_e32 v62, v77, v77
	v_fmac_f32_e32 v61, v58, v58
	v_fmac_f32_e32 v62, v76, v76
	v_add_f32_e32 v61, v61, v62
	v_add_f32_e32 v108, v60, v61
	v_lshlrev_b32_e32 v60, 16, v214
	v_and_b32_e32 v61, 0xffff0000, v214
	v_lshlrev_b32_e32 v62, 16, v215
	v_and_b32_e32 v63, 0xffff0000, v215
	v_pk_add_f32 v[54:55], v[54:55], v[102:103]
	v_pk_add_f32 v[52:53], v[52:53], v[100:101]
	v_lshlrev_b32_e32 v78, 16, v216
	v_and_b32_e32 v79, 0xffff0000, v216
	v_pk_add_f32 v[54:55], v[54:55], v[62:63]
	v_pk_add_f32 v[52:53], v[52:53], v[60:61]
	v_pk_add_f32 v[48:49], v[48:49], v[92:93]
	v_lshlrev_b32_e32 v106, 16, v217
	v_and_b32_e32 v107, 0xffff0000, v217
	v_pk_add_f32 v[50:51], v[50:51], v[94:95]
	v_pk_add_f32 v[62:63], v[48:49], v[78:79]
	v_mul_f32_e32 v48, v53, v53
	v_mul_f32_e32 v49, v55, v55
	v_pk_add_f32 v[60:61], v[50:51], v[106:107]
	v_fmac_f32_e32 v48, v52, v52
	v_fmac_f32_e32 v49, v54, v54
	v_add_f32_e32 v48, v48, v49
	v_mul_f32_e32 v49, v63, v63
	v_mul_f32_e32 v50, v61, v61
	v_fmac_f32_e32 v49, v62, v62
	v_fmac_f32_e32 v50, v60, v60
	v_add_f32_e32 v49, v49, v50
	v_add_f32_e32 v48, v48, v49
	v_add_f32_e32 v48, v108, v48
	ds_bpermute_b32 v49, v174, v48
	v_cvt_pk_bf16_f32 v58, v58, v59
	v_cvt_pk_bf16_f32 v59, v76, v77
	global_store_dwordx4 v[122:123], v[56:59], off
	v_cvt_pk_bf16_f32 v50, v52, v53
	s_waitcnt lgkmcnt(0)
	v_add_f32_e32 v48, v48, v49
	ds_bpermute_b32 v49, v142, v48
	v_cvt_pk_bf16_f32 v51, v54, v55
	v_cvt_pk_bf16_f32 v52, v62, v63
	v_cvt_pk_bf16_f32 v53, v60, v61
	global_store_dwordx4 v[122:123], v[50:53], off offset:256
	s_and_saveexec_b64 s[0:1], s[42:43]
	s_cbranch_execz .LBB0_223
	v_lshlrev_b64 v[50:51], 7, v[120:121]
	v_lshl_add_u64 v[50:51], s[14:15], 0, v[50:51]
	v_lshl_add_u64 v[50:51], s[4:5], 2, v[50:51]
	s_lshl_b32 s22, s57, 2
	v_lshl_add_u64 v[50:51], v[50:51], 0, s[22:23]
	s_waitcnt lgkmcnt(0)
	v_add_f32_e32 v48, v48, v49
	global_store_dword v[50:51], v48, off
.LBB0_223:
	s_or_b64 exec, exec, s[0:1]
	v_or_b32_e32 v192, 48, v120
	v_ashrrev_i32_e32 v193, 31, v192
	s_waitcnt lgkmcnt(0)
	v_lshlrev_b64 v[48:49], 12, v[192:193]
	v_lshl_add_u64 v[48:49], s[16:17], 0, v[48:49]
	v_lshl_add_u64 v[56:57], v[220:221], 1, v[48:49]
	global_load_dwordx4 v[52:55], v[56:57], off
	global_load_dwordx4 v[48:51], v[56:57], off offset:256
	s_waitcnt vmcnt(14)
	v_lshlrev_b32_e32 v58, 16, v194
	v_and_b32_e32 v59, 0xffff0000, v194
	v_pk_add_f32 v[44:45], v[44:45], v[96:97]
	v_lshlrev_b32_e32 v60, 16, v195
	v_and_b32_e32 v61, 0xffff0000, v195
	v_lshlrev_b32_e32 v62, 16, v196
	v_and_b32_e32 v63, 0xffff0000, v196
	v_lshlrev_b32_e32 v76, 16, v197
	v_and_b32_e32 v77, 0xffff0000, v197
	v_pk_add_f32 v[46:47], v[46:47], v[98:99]
	v_pk_add_f32 v[44:45], v[44:45], v[58:59]
	v_pk_add_f32 v[42:43], v[42:43], v[90:91]
	v_pk_add_f32 v[40:41], v[40:41], v[88:89]
	v_pk_add_f32 v[46:47], v[46:47], v[60:61]
	v_pk_add_f32 v[58:59], v[42:43], v[76:77]
	v_pk_add_f32 v[42:43], v[40:41], v[62:63]
	v_cvt_pk_bf16_f32 v40, v44, v45
	v_mul_f32_e32 v45, v45, v45
	v_fmac_f32_e32 v45, v44, v44
	v_mul_f32_e32 v44, v47, v47
	v_fmac_f32_e32 v44, v46, v46
	v_cvt_pk_bf16_f32 v41, v46, v47
	v_add_f32_e32 v44, v45, v44
	v_mul_f32_e32 v45, v43, v43
	v_mul_f32_e32 v46, v59, v59
	v_fmac_f32_e32 v45, v42, v42
	v_fmac_f32_e32 v46, v58, v58
	v_add_f32_e32 v45, v45, v46
	v_add_f32_e32 v76, v44, v45
	v_lshlrev_b32_e32 v44, 16, v230
	v_and_b32_e32 v45, 0xffff0000, v230
	v_lshlrev_b32_e32 v46, 16, v231
	v_and_b32_e32 v47, 0xffff0000, v231
	v_pk_add_f32 v[38:39], v[38:39], v[102:103]
	v_pk_add_f32 v[36:37], v[36:37], v[100:101]
	v_lshlrev_b32_e32 v60, 16, v232
	v_and_b32_e32 v61, 0xffff0000, v232
	v_pk_add_f32 v[38:39], v[38:39], v[46:47]
	v_pk_add_f32 v[36:37], v[36:37], v[44:45]
	v_pk_add_f32 v[32:33], v[32:33], v[92:93]
	v_lshlrev_b32_e32 v62, 16, v233
	v_and_b32_e32 v63, 0xffff0000, v233
	v_pk_add_f32 v[34:35], v[34:35], v[94:95]
	v_pk_add_f32 v[46:47], v[32:33], v[60:61]
	v_mul_f32_e32 v32, v37, v37
	v_mul_f32_e32 v33, v39, v39
	v_pk_add_f32 v[44:45], v[34:35], v[62:63]
	v_fmac_f32_e32 v32, v36, v36
	v_fmac_f32_e32 v33, v38, v38
	v_add_f32_e32 v32, v32, v33
	v_mul_f32_e32 v33, v47, v47
	v_mul_f32_e32 v34, v45, v45
	v_fmac_f32_e32 v33, v46, v46
	v_fmac_f32_e32 v34, v44, v44
	v_add_f32_e32 v33, v33, v34
	v_add_f32_e32 v32, v32, v33
	v_add_f32_e32 v32, v76, v32
	ds_bpermute_b32 v33, v174, v32
	v_cvt_pk_bf16_f32 v42, v42, v43
	v_cvt_pk_bf16_f32 v43, v58, v59
	global_store_dwordx4 v[104:105], v[40:43], off
	v_cvt_pk_bf16_f32 v34, v36, v37
	s_waitcnt lgkmcnt(0)
	v_add_f32_e32 v32, v32, v33
	ds_bpermute_b32 v33, v142, v32
	v_cvt_pk_bf16_f32 v35, v38, v39
	v_cvt_pk_bf16_f32 v36, v46, v47
	v_cvt_pk_bf16_f32 v37, v44, v45
	global_store_dwordx4 v[104:105], v[34:37], off offset:256
	s_and_saveexec_b64 s[0:1], s[42:43]
	s_cbranch_execz .LBB0_225
	v_or_b32_e32 v34, 16, v120
	v_ashrrev_i32_e32 v35, 31, v34
	v_lshlrev_b64 v[34:35], 7, v[34:35]
	v_lshl_add_u64 v[34:35], s[14:15], 0, v[34:35]
	v_lshl_add_u64 v[34:35], s[4:5], 2, v[34:35]
	s_lshl_b32 s22, s57, 2
	v_lshl_add_u64 v[34:35], v[34:35], 0, s[22:23]
	s_waitcnt lgkmcnt(0)
	v_add_f32_e32 v32, v32, v33
	global_store_dword v[34:35], v32, off
